# attention K tile LDS row stride 272->288 B (conflict-free ds_read_b128 of K fragments), V tiles shifted accordingly
# speedup vs baseline: 1.0058x; 1.0058x over previous
.LBB0_3:
	s_add_u32 s2, s0, 0xa0
	s_addc_u32 s3, s1, 0
	v_writelane_b32 v254, s2, 1
	v_lshrrev_b32_e32 v1, 20, v0
	v_lshrrev_b32_e32 v0, 10, v0
	v_writelane_b32 v254, s3, 2
	v_or_b32_e32 v0, v0, v1
	v_readlane_b32 s3, v254, 0
	s_lshl_b32 s2, s3, 3
	v_writelane_b32 v254, s2, 3
	s_lshl_b32 s2, s3, 9
	s_cmpk_lt_i32 s3, 0x80
	v_writelane_b32 v254, s2, 4
	s_cselect_b64 s[4:5], -1, 0
	v_writelane_b32 v254, s4, 5
	s_movk_i32 s2, 0x3ff
	v_and_or_b32 v0, v0, s2, v135
	v_writelane_b32 v254, s5, 6
	s_lshl_b32 s2, s3, 11
	v_writelane_b32 v254, s2, 7
	s_lshl_b32 s2, s3, 6
	v_writelane_b32 v254, s2, 8
	s_add_i32 s2, 0, 0x186a8
	v_writelane_b32 v254, s2, 9
	s_add_i32 s2, 0, 0x186b0
	v_writelane_b32 v254, s2, 10
	s_add_i32 s2, 0, 0x186b8
	v_writelane_b32 v254, s2, 11
	s_add_i32 s2, 0, 0x186c0
	v_writelane_b32 v254, s2, 12
	s_add_i32 s2, 0, 0x186c8
	v_writelane_b32 v254, s2, 13
	s_add_i32 s2, 0, 0x186d0
	v_writelane_b32 v254, s2, 14
	s_add_i32 s2, 0, 0x186d8
	v_writelane_b32 v254, s2, 15
	s_add_i32 s2, 0, 0x186a4
	v_writelane_b32 v254, s2, 16
	s_add_i32 s2, 0, 0x186ac
	v_writelane_b32 v254, s2, 17
	s_add_i32 s2, 0, 0x186b4
	v_writelane_b32 v254, s2, 18
	s_add_i32 s2, 0, 0x186bc
	v_writelane_b32 v254, s2, 19
	s_add_i32 s2, 0, 0x186c4
	v_writelane_b32 v254, s2, 20
	s_add_i32 s2, 0, 0x186cc
	v_writelane_b32 v254, s2, 21
	s_add_i32 s2, 0, 0x186d4
	v_writelane_b32 v254, s2, 22
	s_add_i32 s2, 0, 0x186dc
	v_writelane_b32 v254, s2, 23
	s_add_i32 s2, 0, 0x186e0
	v_writelane_b32 v254, s2, 24
	s_add_i32 s2, 0, 0x186e4
	v_writelane_b32 v254, s2, 25
	s_add_i32 s2, 0, 0x186e8
	v_writelane_b32 v254, s2, 26
	s_add_i32 s2, 0, 0x186ec
	v_writelane_b32 v254, s2, 27
	s_add_i32 s2, 0, 0x186f0
	v_writelane_b32 v254, s2, 28
	s_add_i32 s2, 0, 0x186f4
	v_writelane_b32 v254, s2, 29
	s_add_i32 s2, 0, 0x186f8
	v_writelane_b32 v254, s2, 30
	s_add_i32 s2, 0, 0x186fc
	v_writelane_b32 v254, s2, 31
	s_add_i32 s2, 0, 0x5000
	v_writelane_b32 v254, s2, 32
	s_add_i32 s2, 0, 0x20040
	v_writelane_b32 v254, s2, 33
	s_add_i32 s2, 0, 0x20044
	v_writelane_b32 v254, s2, 34
	v_cmp_eq_u32_e64 s[2:3], 0, v0
	s_mov_b32 s90, 0x9000
	s_movk_i32 s43, 0x1f8
	v_writelane_b32 v254, s2, 35
	v_mov_b32_e32 v133, 0
	s_mov_b32 s92, 0xffff0000
	v_writelane_b32 v254, s3, 36
	v_mov_b32_e32 v137, 0x358637bd
	s_mov_b32 s94, 0x800000
	s_movk_i32 s27, 0x2000
	s_movk_i32 s96, 0xa00
	s_add_i32 s62, 0, 0x20000
	v_mov_b32_e32 v192, 0x629c000
	s_add_i32 s69, 0, 0x186a0
	v_mov_b32_e32 v193, 0x260
	v_mov_b32_e32 v194, 0x3a83126f
	s_add_i32 s91, 0, 0x4800
	s_add_i32 s57, 0, 0xd000
	s_add_i32 s70, 0, 0x9000
	v_mov_b32_e32 v134, 0xbf1f24be
	v_mov_b32_e32 v136, 0x3e642e9d
	v_mov_b32_e32 v195, 0x1f8
	v_mov_b32_e32 v196, 0x3f4ccccd
	v_mov_b32_e32 v197, 0x3e91f4c4
	v_mov_b32_e32 v198, 0x3c0881c4
	v_mov_b32_e32 v199, 0xbab64f3b
	v_mov_b32_e32 v215, 0x1000
	v_mov_b32_e32 v205, 1
	v_mov_b64_e32 v[138:139], 0x2bf
	v_mov_b64_e32 v[140:141], 0x2c0
	v_mov_b32_e32 v204, 0x1400
	v_mov_b32_e32 v206, 0xa00
	v_mov_b32_e32 v207, 0x7fc00000
	v_mov_b32_e32 v208, 0x800
	v_mov_b64_e32 v[142:143], 0x57f
	v_mov_b64_e32 v[144:145], 0x580
	v_mov_b32_e32 v209, 0x7f800000
	v_mov_b32_e32 v210, 0x461c4000
	v_mov_b32_e32 v211, 0x37000000
	v_not_b32_e32 v212, 63
	v_not_b32_e32 v213, 31
	v_mov_b64_e32 v[146:147], 0x100
	v_mov_b64_e32 v[148:149], 0xff
	v_mov_b32_e32 v214, 0xffffe000
	s_mov_b32 s28, 0x7f800000
	s_movk_i32 s95, 0x404
	s_movk_i32 s72, 0x2800
	s_movk_i32 s73, 0x1600
	s_movk_i32 s56, 0x5800
	s_mov_b32 s38, 0
	s_mov_b32 s59, 0
	s_mov_b64 s[30:31], 0x1000
	s_mov_b64 s[66:67], 0x80
	s_mov_b64 s[74:75], 0x10000
	s_mov_b64 s[76:77], 0x4000
	s_mov_b64 s[22:23], 0x87000
	s_mov_b64 s[24:25], 0x90000
	s_mov_b64 s[20:21], 0x800
	v_writelane_b32 v254, s51, 37
	s_branch .LBB0_6

.LBB0_63:
	s_cmp_gt_i32 s71, 2
	s_mov_b64 s[2:3], -1
	s_cbranch_scc0 .LBB0_1082
	s_cmp_gt_i32 s71, 3
	s_cbranch_scc0 .LBB0_134
	s_mov_b64 s[2:3], s[0:1]
	s_load_dword s24, s[2:3], 0x98
	s_cmpk_gt_i32 s55, 0x7f
	s_movk_i32 s43, 0x120
	s_cbranch_scc1 .LBB0_74
	s_waitcnt lgkmcnt(0)
	s_bitcmp0_b32 s24, 6
	v_readlane_b32 s4, v254, 55
	s_cselect_b64 s[2:3], -1, 0
	v_readlane_b32 s5, v254, 56
	s_or_b64 s[2:3], s[4:5], s[2:3]
	s_andn2_b64 vcc, exec, s[2:3]
	s_cbranch_vccnz .LBB0_74
	s_waitcnt vmcnt(0)
	v_mov_b32_e32 v15, v135
	s_bfe_u32 s58, s55, 0x10005
	v_lshlrev_b32_e32 v0, 4, v15
	v_add_u32_e32 v1, 0x2000, v0
	v_ashrrev_i32_e32 v2, 31, v1
	v_lshrrev_b32_e32 v2, 22, v2
	v_add_u32_e32 v2, v1, v2
	v_ashrrev_i32_e32 v2, 10, v2
	v_mul_i32_i24_e32 v3, 0x400, v2
	v_sub_u32_e32 v1, v1, v3
	v_lshrrev_b32_e32 v3, 4, v1
	v_bitop3_b32 v1, v3, v1, 32 bitop3:0x6c
	v_ashrrev_i32_e32 v3, 31, v1
	v_lshrrev_b32_e32 v3, 26, v3
	s_min_i32 s2, s55, 64
	v_add_u32_e32 v3, v1, v3
	s_and_b32 s3, s55, 31
	s_and_b32 s2, s2, 7
	s_bfe_u32 s8, s55, 0x20003
	s_lshl_b32 s9, s58, 22
	v_ashrrev_i32_e32 v4, 6, v3
	v_and_b32_e32 v3, 0xc0, v3
	s_cmp_lt_i32 s55, 64
	v_sub_u32_e32 v1, v1, v3
	s_cselect_b64 s[6:7], -1, 0
	v_ashrrev_i16_sdwa v1, v205, sext(v1) dst_sel:DWORD dst_unused:UNUSED_PAD src0_sel:DWORD src1_sel:BYTE_0
	s_and_b64 s[4:5], s[6:7], exec
	v_lshlrev_b32_e32 v5, 3, v2
	v_bfe_i32 v14, v1, 0, 16
	v_bfe_i32 v1, v15, 27, 1
	s_cselect_b32 s4, s8, s3
	s_mov_b32 s3, 0x5200000
	s_cselect_b32 s15, 11, 8
	v_and_b32_e32 v5, 0x7ffffff0, v5
	v_lshlrev_b32_e32 v2, 5, v2
	v_lshrrev_b32_e32 v1, 22, v1
	s_cselect_b32 s18, s3, 0x6200000
	s_mov_b32 s3, 0xeea4400
	s_movk_i32 s5, 0x100
	v_add_lshl_u32 v12, v4, v5, s15
	v_and_b32_e32 v13, 32, v2
	v_add_u32_e32 v1, v0, v1
	s_cselect_b32 s3, s3, 0xf6a4400
	s_cselect_b32 s19, 0x800, s5
	s_cselect_b32 s5, 23, 17
	s_cselect_b32 s8, 20, 17
	s_add_u32 s10, s80, s18
	v_or_b32_e32 v2, v12, v13
	v_and_b32_e32 v1, 0xfffffc00, v1
	s_addc_u32 s11, s81, 0
	s_lshl_b64 s[12:13], s[58:59], s5
	v_add_lshl_u32 v128, v2, v14, 1
	v_sub_u32_e32 v0, v0, v1
	v_ashrrev_i32_e32 v2, 31, v15
	s_add_u32 s10, s10, s12
	v_lshrrev_b32_e32 v1, 4, v0
	v_lshrrev_b32_e32 v2, 26, v2
	s_addc_u32 s11, s11, s13
	v_bitop3_b32 v1, v1, v0, 32 bitop3:0x6c
	v_ashrrev_i32_e32 v0, 31, v0
	v_add_u32_e32 v2, v15, v2
	s_add_u32 s3, s80, s3
	v_lshrrev_b32_e32 v0, 26, v0
	v_ashrrev_i32_e32 v2, 6, v2
	s_addc_u32 s5, s81, 0
	v_add_u32_e32 v0, v1, v0
	v_lshlrev_b32_e32 v3, 3, v2
	v_readfirstlane_b32 s14, v15
	s_add_u32 s27, s3, s9
	v_ashrrev_i32_e32 v0, 6, v0
	v_and_b32_e32 v3, 0x7ffffff0, v3
	s_addc_u32 s28, s5, 0
	s_ashr_i32 s22, s14, 6
	v_add_lshl_u32 v16, v0, v3, s15
	v_mul_i32_i24_e32 v0, 64, v0
	s_mov_b32 s3, s59
	s_mov_b32 s5, s59
	s_ashr_i32 s23, s14, 8
	s_lshl_b32 s25, s19, 8
	s_lshl_b32 s26, s22, 10
	v_lshlrev_b32_e32 v2, 5, v2
	v_sub_u32_e32 v0, v1, v0
	s_lshl_b64 s[16:17], s[2:3], s8
	s_lshl_b64 s[8:9], s[4:5], s8
	v_and_b32_e32 v17, 32, v2
	v_ashrrev_i16_sdwa v0, v205, sext(v0) dst_sel:DWORD dst_unused:UNUSED_PAD src0_sel:DWORD src1_sel:BYTE_0
	s_add_u32 s8, s27, s8
	v_or_b32_e32 v2, v16, v17
	v_bfe_i32 v18, v0, 0, 16
	s_addc_u32 s9, s28, s9
	s_add_i32 s3, s26, 0
	v_add_lshl_u32 v132, v2, v18, 1
	s_add_i32 m0, s3, 0x10000
	v_mov_b32_e32 v129, v133
	global_load_lds_dwordx4 v132, s[8:9]
	s_add_i32 m0, s3, 0x12000
	s_add_u32 s10, s10, s16
	global_load_lds_dwordx4 v128, s[8:9]
	s_addc_u32 s11, s11, s17
	s_mov_b32 m0, s3
	s_add_i32 s5, s3, 0x2000
	global_load_lds_dwordx4 v132, s[10:11]
	s_mov_b32 m0, s5
	s_add_u32 s28, s8, s25
	global_load_lds_dwordx4 v128, s[10:11]
	s_addc_u32 s29, s9, 0
	s_add_i32 m0, s3, 0x14000
	v_lshl_add_u64 v[8:9], s[28:29], 0, v[132:133]
	global_load_lds_dwordx4 v132, s[28:29]
	s_add_i32 m0, s3, 0x16000
	s_add_u32 s30, s10, s25
	s_addc_u32 s31, s11, 0
	s_add_i32 s27, s3, 0x4000
	v_lshl_add_u64 v[10:11], s[28:29], 0, v[128:129]
	global_load_lds_dwordx4 v128, s[28:29]
	s_mov_b32 m0, s27
	s_add_i32 s28, s3, 0x6000
	global_load_lds_dwordx4 v132, s[30:31]
	s_mov_b32 m0, s28
	v_lshl_add_u64 v[0:1], s[8:9], 0, v[132:133]
	global_load_lds_dwordx4 v128, s[30:31]
	v_lshl_add_u64 v[2:3], s[8:9], 0, v[128:129]
	v_lshl_add_u64 v[4:5], s[10:11], 0, v[132:133]
	v_lshl_add_u64 v[6:7], s[10:11], 0, v[128:129]
	s_cmp_lg_u32 s23, 1
	s_cbranch_scc1 .LBB0_69
	s_barrier

.LBB0_124:
	v_cmp_gt_f32_e32 vcc, 0, v18
	v_cmp_ngt_f32_e64 s[4:5], 0, v18
	v_mul_lo_u32 v116, v36, s43
	v_lshlrev_b32_e32 v117, 5, v37
	s_and_saveexec_b64 s[24:25], s[4:5]
	s_xor_b64 s[4:5], exec, s[24:25]
	v_mul_lo_u32 v116, v36, s43
	v_lshlrev_b32_e32 v117, 5, v37
	s_or_saveexec_b64 s[4:5], s[4:5]
	v_mul_u32_u24_e32 v16, 0x120, v41
	v_add_u32_e32 v118, v16, v132
	v_lshlrev_b32_e32 v16, 4, v37
	v_mov_b32_e32 v21, 0xff800000
	v_lshl_add_u64 v[24:25], s[18:19], 0, v[34:35]
	v_lshlrev_b32_e32 v132, 1, v16
	v_mov_b32_e32 v16, 0xff800000
	s_xor_b64 exec, exec, s[4:5]
	s_cbranch_execz .LBB0_130
	v_lshl_add_u64 v[16:17], v[24:25], 0, v[132:133]
	global_load_dwordx4 v[26:29], v[16:17], off offset:16
	global_load_dwordx4 v[34:37], v[16:17], off
	v_add3_u32 v16, 0, v116, v117
	s_mov_b32 s18, 1
	v_mov_b32_e32 v19, 0xff800000
	v_mov_b32_e32 v21, 0xff800000
	s_waitcnt vmcnt(0)
	ds_write_b128 v16, v[34:37]
	ds_write_b128 v16, v[26:29] offset:16
	v_lshl_add_u64 v[16:17], v[32:33], 0, s[76:77]
	s_waitcnt lgkmcnt(0)
	s_barrier
.LBB0_128:
	global_load_dwordx4 v[26:29], v[16:17], off offset:16
	global_load_dwordx4 v[34:37], v[16:17], off
	s_bitcmp1_b32 s18, 0
	s_cselect_b32 s19, 0, s91
	v_add_u32_e32 v22, s19, v118
	ds_read_b128 v[42:45], v22
	ds_read_b128 v[46:49], v22 offset:64
	ds_read_b128 v[50:53], v22 offset:128
	ds_read_b128 v[54:57], v22 offset:192
	ds_read_b128 v[58:61], v22 offset:4608
	ds_read_b128 v[62:65], v22 offset:4672
	ds_read_b128 v[66:69], v22 offset:4736
	ds_read_b128 v[70:73], v22 offset:4800
	ds_read_b128 v[74:77], v22 offset:9216
	ds_read_b128 v[78:81], v22 offset:9280
	ds_read_b128 v[82:85], v22 offset:9344
	ds_read_b128 v[86:89], v22 offset:9408
	ds_read_b128 v[90:93], v22 offset:13824
	ds_read_b128 v[94:97], v22 offset:13888
	ds_read_b128 v[98:101], v22 offset:13952
	ds_read_b128 v[106:109], v22 offset:14016
	s_waitcnt lgkmcnt(14)
	v_mfma_f32_16x16x32_bf16 v[42:45], v[42:45], v[12:15], 0
	v_mfma_f32_16x16x32_bf16 v[42:45], v[46:49], v[0:3], v[42:45]
	s_waitcnt lgkmcnt(13)
	v_mfma_f32_16x16x32_bf16 v[46:49], v[50:53], v[4:7], 0
	s_waitcnt lgkmcnt(12)
	v_mfma_f32_16x16x32_bf16 v[46:49], v[54:57], v[8:11], v[46:49]
	s_waitcnt lgkmcnt(11)
	v_mfma_f32_16x16x32_bf16 v[50:53], v[58:61], v[12:15], 0
	s_waitcnt lgkmcnt(9)
	v_mfma_f32_16x16x32_bf16 v[54:57], v[66:69], v[4:7], 0
	v_mfma_f32_16x16x32_bf16 v[50:53], v[62:65], v[0:3], v[50:53]
	s_waitcnt lgkmcnt(8)
	v_mfma_f32_16x16x32_bf16 v[54:57], v[70:73], v[8:11], v[54:57]
	s_waitcnt lgkmcnt(7)
	v_mfma_f32_16x16x32_bf16 v[58:61], v[74:77], v[12:15], 0
	s_waitcnt lgkmcnt(5)
	v_mfma_f32_16x16x32_bf16 v[62:65], v[82:85], v[4:7], 0
	s_waitcnt lgkmcnt(3)
	v_mfma_f32_16x16x32_bf16 v[66:69], v[90:93], v[12:15], 0
	s_waitcnt lgkmcnt(1)
	v_mfma_f32_16x16x32_bf16 v[70:73], v[98:101], v[4:7], 0
	v_mfma_f32_16x16x32_bf16 v[58:61], v[78:81], v[0:3], v[58:61]
	v_mfma_f32_16x16x32_bf16 v[62:65], v[86:89], v[8:11], v[62:65]
	v_mfma_f32_16x16x32_bf16 v[66:69], v[94:97], v[0:3], v[66:69]
	s_waitcnt lgkmcnt(0)
	v_mfma_f32_16x16x32_bf16 v[70:73], v[106:109], v[8:11], v[70:73]
	v_max_f32_e32 v22, v43, v43
	v_max_f32_e32 v23, v42, v42
	v_max_f32_e32 v22, v23, v22
	v_max_f32_e32 v23, v45, v45
	v_max_f32_e32 v30, v44, v44
	v_max_f32_e32 v23, v30, v23
	v_max_f32_e32 v30, v53, v53
	v_max_f32_e32 v31, v52, v52
	v_max_f32_e32 v30, v31, v30
	v_max3_f32 v30, v50, v51, v30
	v_max3_f32 v22, v22, v23, v30
	v_max_f32_e32 v23, v59, v59
	v_max_f32_e32 v30, v58, v58
	v_max_f32_e32 v23, v30, v23
	v_max_f32_e32 v30, v61, v61
	v_max_f32_e32 v31, v60, v60
	v_max_f32_e32 v30, v31, v30
	v_max_f32_e32 v31, v69, v69
	v_max_f32_e32 v38, v68, v68
	v_max_f32_e32 v31, v38, v31
	v_max3_f32 v31, v66, v67, v31
	v_max3_f32 v23, v23, v30, v31
	v_max3_f32 v19, v19, v22, v23
	v_max_f32_e32 v22, v47, v47
	v_max_f32_e32 v23, v46, v46
	v_max_f32_e32 v22, v23, v22
	v_max_f32_e32 v23, v49, v49
	v_max_f32_e32 v30, v48, v48
	v_max_f32_e32 v23, v30, v23
	v_max_f32_e32 v30, v57, v57
	v_max_f32_e32 v31, v56, v56
	v_max_f32_e32 v30, v31, v30
	v_max3_f32 v30, v54, v55, v30
	v_max3_f32 v22, v22, v23, v30
	v_max_f32_e32 v23, v63, v63
	v_max_f32_e32 v30, v62, v62
	v_max_f32_e32 v23, v30, v23
	v_max_f32_e32 v30, v65, v65
	v_max_f32_e32 v31, v64, v64
	v_max_f32_e32 v30, v31, v30
	v_max_f32_e32 v31, v73, v73
	v_max_f32_e32 v38, v72, v72
	v_max_f32_e32 v31, v38, v31
	v_max3_f32 v31, v70, v71, v31
	v_max3_f32 v23, v23, v30, v31
	s_cselect_b32 s19, s91, 0
	s_add_i32 s18, s18, 1
	v_max3_f32 v21, v21, v22, v23
	v_add3_u32 v22, s19, v116, v117
	s_cmp_lg_u32 s23, s18
	v_lshl_add_u64 v[16:17], v[16:17], 0, s[76:77]
	s_waitcnt vmcnt(0)
	ds_write_b128 v22, v[34:37]
	ds_write_b128 v22, v[26:29] offset:16
	s_waitcnt lgkmcnt(0)
	s_barrier
	s_cbranch_scc1 .LBB0_128
	v_add_u32_e32 v16, s19, v118
	ds_read_b128 v[26:29], v16
	ds_read_b128 v[34:37], v16 offset:64
	ds_read_b128 v[42:45], v16 offset:128
	ds_read_b128 v[46:49], v16 offset:192
	ds_read_b128 v[50:53], v16 offset:4608
	ds_read_b128 v[54:57], v16 offset:4672
	ds_read_b128 v[58:61], v16 offset:4736
	ds_read_b128 v[62:65], v16 offset:4800
	ds_read_b128 v[66:69], v16 offset:9216
	ds_read_b128 v[70:73], v16 offset:9280
	ds_read_b128 v[74:77], v16 offset:9344
	ds_read_b128 v[78:81], v16 offset:9408
	ds_read_b128 v[82:85], v16 offset:13824
	ds_read_b128 v[86:89], v16 offset:13888
	ds_read_b128 v[90:93], v16 offset:13952
	ds_read_b128 v[94:97], v16 offset:14016
	s_waitcnt lgkmcnt(14)
	v_mfma_f32_16x16x32_bf16 v[26:29], v[26:29], v[12:15], 0
	v_mfma_f32_16x16x32_bf16 v[26:29], v[34:37], v[0:3], v[26:29]
	s_waitcnt lgkmcnt(13)
	v_mfma_f32_16x16x32_bf16 v[34:37], v[42:45], v[4:7], 0
	s_waitcnt lgkmcnt(12)
	v_mfma_f32_16x16x32_bf16 v[34:37], v[46:49], v[8:11], v[34:37]
	s_waitcnt lgkmcnt(11)
	v_mfma_f32_16x16x32_bf16 v[42:45], v[50:53], v[12:15], 0
	s_waitcnt lgkmcnt(9)
	v_mfma_f32_16x16x32_bf16 v[46:49], v[58:61], v[4:7], 0
	v_mfma_f32_16x16x32_bf16 v[42:45], v[54:57], v[0:3], v[42:45]
	s_waitcnt lgkmcnt(8)
	v_mfma_f32_16x16x32_bf16 v[46:49], v[62:65], v[8:11], v[46:49]
	s_waitcnt lgkmcnt(7)
	v_mfma_f32_16x16x32_bf16 v[50:53], v[66:69], v[12:15], 0
	s_waitcnt lgkmcnt(5)
	v_mfma_f32_16x16x32_bf16 v[54:57], v[74:77], v[4:7], 0
	s_waitcnt lgkmcnt(3)
	v_mfma_f32_16x16x32_bf16 v[58:61], v[82:85], v[12:15], 0
	s_waitcnt lgkmcnt(1)
	v_mfma_f32_16x16x32_bf16 v[62:65], v[90:93], v[4:7], 0
	v_mfma_f32_16x16x32_bf16 v[50:53], v[70:73], v[0:3], v[50:53]
	v_mfma_f32_16x16x32_bf16 v[54:57], v[78:81], v[8:11], v[54:57]
	v_mfma_f32_16x16x32_bf16 v[58:61], v[86:89], v[0:3], v[58:61]
	s_waitcnt lgkmcnt(0)
	v_mfma_f32_16x16x32_bf16 v[62:65], v[94:97], v[8:11], v[62:65]
	v_max_f32_e32 v16, v27, v27
	v_max_f32_e32 v17, v26, v26
	v_max_f32_e32 v16, v17, v16
	v_max_f32_e32 v17, v29, v29
	v_max_f32_e32 v22, v28, v28
	v_max_f32_e32 v17, v22, v17
	v_max_f32_e32 v22, v45, v45
	v_max_f32_e32 v23, v44, v44
	v_max_f32_e32 v22, v23, v22
	v_max3_f32 v22, v42, v43, v22
	v_max3_f32 v16, v16, v17, v22
	v_max_f32_e32 v17, v51, v51
	v_max_f32_e32 v22, v50, v50
	v_max_f32_e32 v17, v22, v17
	v_max_f32_e32 v22, v53, v53
	v_max_f32_e32 v23, v52, v52
	v_max_f32_e32 v22, v23, v22
	v_max_f32_e32 v23, v61, v61
	v_max_f32_e32 v26, v60, v60
	v_max_f32_e32 v23, v26, v23
	v_max3_f32 v23, v58, v59, v23
	v_max3_f32 v17, v17, v22, v23
	v_max3_f32 v16, v19, v16, v17
	v_max_f32_e32 v17, v35, v35
	v_max_f32_e32 v19, v34, v34
	v_max_f32_e32 v17, v19, v17
	v_max_f32_e32 v19, v37, v37
	v_max_f32_e32 v22, v36, v36
	v_max_f32_e32 v19, v22, v19
	v_max_f32_e32 v22, v49, v49
	v_max_f32_e32 v23, v48, v48
	v_max_f32_e32 v22, v23, v22
	v_max3_f32 v22, v46, v47, v22
	v_max3_f32 v17, v17, v19, v22
	v_max_f32_e32 v19, v55, v55
	v_max_f32_e32 v22, v54, v54
	v_max_f32_e32 v19, v22, v19
	v_max_f32_e32 v22, v57, v57
	v_max_f32_e32 v23, v56, v56
	v_max_f32_e32 v22, v23, v22
	v_max_f32_e32 v23, v65, v65
	v_max_f32_e32 v26, v64, v64
	v_max_f32_e32 v23, v26, v23
	v_max3_f32 v23, v62, v63, v23
	v_max3_f32 v19, v19, v22, v23
	v_max3_f32 v21, v21, v17, v19
	s_barrier
.LBB0_130:
	s_or_b64 exec, exec, s[4:5]
	v_ashrrev_i32_e32 v42, 2, v40
	v_and_b32_e32 v36, 3, v40
	v_lshrrev_b32_e32 v26, 1, v40
	v_bfe_u32 v27, v40, 1, 3
	v_mad_i64_i32 v[34:35], s[4:5], s34, v42, 0
	v_bitop3_b32 v26, v105, v26, 7 bitop3:0x78
	v_bitop3_b32 v27, v105, v27, 4 bitop3:0x36
	v_lshl_add_u64 v[28:29], v[24:25], 0, v[132:133]
	v_lshl_add_u64 v[34:35], v[34:35], 1, s[16:17]
	v_lshlrev_b32_e32 v132, 5, v36
	v_lshlrev_b32_e32 v121, 4, v26
	v_lshlrev_b32_e32 v119, 4, v27
	global_load_dwordx4 v[24:27], v[28:29], off offset:16
	s_nop 0
	global_load_dwordx4 v[28:31], v[28:29], off
	v_lshl_add_u64 v[38:39], v[34:35], 0, v[132:133]
	v_lshrrev_b32_e32 v17, 3, v40
	v_bfe_u32 v19, v40, 3, 3
	v_lshlrev_b32_e32 v23, 1, v36
	v_lshlrev_b32_e32 v120, 7, v41
	global_load_dwordx4 v[34:37], v[38:39], off offset:16
	s_nop 0
	global_load_dwordx4 v[38:41], v[38:39], off
	v_lshlrev_b32_e32 v22, 7, v42
	v_bitop3_b32 v17, v23, v17, 7 bitop3:0x78
	v_lshl_or_b32 v122, v17, 4, v22
	v_bitop3_b32 v17, v23, v19, 1 bitop3:0x36
	v_lshl_or_b32 v123, v17, 4, v22
	ds_bpermute_b32 v17, v114, v16
	ds_bpermute_b32 v22, v114, v21
	v_max_f32_e32 v16, v16, v16
	v_max_f32_e32 v21, v21, v21
	v_add3_u32 v43, 0, v116, v117
	s_waitcnt lgkmcnt(1)
	v_max_f32_e32 v17, v17, v17
	s_waitcnt lgkmcnt(0)
	v_max_f32_e32 v22, v22, v22
	v_max_f32_e32 v16, v16, v17
	v_max_f32_e32 v21, v21, v22
	ds_bpermute_b32 v17, v115, v16
	ds_bpermute_b32 v22, v115, v21
	s_add_i32 s23, s23, -1
	s_waitcnt vmcnt(2)
	ds_write_b128 v43, v[28:31]
	ds_write_b128 v43, v[24:27] offset:16
	v_add_u32_e32 v24, 0, v122
	s_waitcnt lgkmcnt(3)
	v_max_f32_e32 v17, v17, v17
	s_waitcnt lgkmcnt(2)
	v_max_f32_e32 v22, v22, v22
	v_max_f32_e32 v16, v16, v17
	v_max_f32_e32 v21, v21, v22
	s_waitcnt vmcnt(0)
	ds_write_b128 v24, v[38:41] offset:36864
	v_add_u32_e32 v24, 0, v123
	ds_write_b128 v24, v[34:37] offset:36864
	v_lshlrev_b32_e32 v24, 1, v42
	v_mad_i64_i32 v[24:25], s[4:5], v24, s34, v[132:133]
	v_cndmask_b32_e32 v16, v18, v16, vcc
	v_cndmask_b32_e32 v20, v20, v21, vcc
	v_lshl_add_u64 v[24:25], s[16:17], 0, v[24:25]
	s_mov_b64 s[4:5], 0x90
	v_xor_b32_e32 v16, 0x80000000, v16
	v_xor_b32_e32 v20, 0x80000000, v20
	v_lshl_add_u64 v[106:107], v[24:25], 0, s[4:5]
	s_mov_b64 s[4:5], 0x4010
	v_mov_b32_e32 v24, 0
	v_mov_b32_e32 v17, v16
	v_mov_b32_e32 v18, v16
	v_mov_b32_e32 v19, v16
	v_mov_b32_e32 v21, v20
	v_mov_b32_e32 v22, v20
	v_mov_b32_e32 v23, v20
	v_lshl_add_u64 v[108:109], v[32:33], 0, s[4:5]
	s_mov_b32 s4, 0
	v_mov_b32_e32 v25, v24
	v_mov_b32_e32 v26, v24
	v_mov_b32_e32 v27, v24
	v_mov_b32_e32 v28, v24
	v_mov_b32_e32 v29, v24
	v_mov_b32_e32 v30, v24
	v_mov_b32_e32 v31, v24
	v_mov_b32_e32 v32, v24
	v_mov_b32_e32 v33, v24
	v_mov_b32_e32 v34, v24
	v_mov_b32_e32 v35, v24
	v_mov_b32_e32 v36, v24
	v_mov_b32_e32 v37, v24
	v_mov_b32_e32 v38, v24
	v_mov_b32_e32 v39, v24
	v_mov_b32_e32 v56, v24
	v_mov_b32_e32 v57, v24
	v_mov_b32_e32 v58, v24
	v_mov_b32_e32 v59, v24
	v_mov_b32_e32 v60, v24
	v_mov_b32_e32 v61, v24
	v_mov_b32_e32 v62, v24
	v_mov_b32_e32 v63, v24
	v_mov_b32_e32 v68, v24
	v_mov_b32_e32 v69, v24
	v_mov_b32_e32 v70, v24
	v_mov_b32_e32 v71, v24
	v_mov_b32_e32 v72, v24
	v_mov_b32_e32 v73, v24
	v_mov_b32_e32 v74, v24
	v_mov_b32_e32 v75, v24
	v_mov_b32_e32 v40, v24
	v_mov_b32_e32 v41, v24
	v_mov_b32_e32 v42, v24
	v_mov_b32_e32 v43, v24
	v_mov_b32_e32 v44, v24
	v_mov_b32_e32 v45, v24
	v_mov_b32_e32 v46, v24
	v_mov_b32_e32 v47, v24
	v_mov_b32_e32 v48, v24
	v_mov_b32_e32 v49, v24
	v_mov_b32_e32 v50, v24
	v_mov_b32_e32 v51, v24
	v_mov_b32_e32 v52, v24
	v_mov_b32_e32 v53, v24
	v_mov_b32_e32 v54, v24
	v_mov_b32_e32 v55, v24
	v_mov_b32_e32 v64, v24
	v_mov_b32_e32 v65, v24
	v_mov_b32_e32 v66, v24
	v_mov_b32_e32 v67, v24
	v_mov_b32_e32 v76, v24
	v_mov_b32_e32 v77, v24
	v_mov_b32_e32 v78, v24
	v_mov_b32_e32 v79, v24
	v_mov_b32_e32 v80, v24
	v_mov_b32_e32 v81, v24
	v_mov_b32_e32 v82, v24
	v_mov_b32_e32 v83, v24
	v_mov_b32_e32 v84, v24
	v_mov_b32_e32 v85, v24
	v_mov_b32_e32 v86, v24
	v_mov_b32_e32 v87, v24
	v_mov_b32_e32 v110, v24
	v_mov_b32_e32 v111, v24
	s_waitcnt lgkmcnt(0)
	s_barrier
.LBB0_131:
	global_load_dwordx4 v[88:91], v[108:109], off
	global_load_dwordx4 v[92:95], v[108:109], off offset:-16
	global_load_dwordx4 v[96:99], v[106:107], off
	global_load_dwordx4 v[100:103], v[106:107], off offset:-16
	s_add_i32 s5, s4, 1
	s_bitcmp1_b32 s4, 0
	s_cselect_b32 s4, s91, 0
	v_add_u32_e32 v132, s4, v118
	ds_read_b128 v[124:127], v132
	ds_read_b128 v[128:131], v132 offset:64
	ds_read_b128 v[150:153], v132 offset:128
	ds_read_b128 v[154:157], v132 offset:192
	ds_read_b128 v[158:161], v132 offset:4608
	ds_read_b128 v[162:165], v132 offset:4672
	ds_read_b128 v[166:169], v132 offset:4736
	ds_read_b128 v[170:173], v132 offset:4800
	ds_read_b128 v[174:177], v132 offset:9216
	ds_read_b128 v[178:181], v132 offset:9280
	ds_read_b128 v[182:185], v132 offset:9344
	ds_read_b128 v[186:189], v132 offset:9408
	ds_read_b128 v[216:219], v132 offset:13824
	ds_read_b128 v[220:223], v132 offset:13888
	ds_read_b128 v[224:227], v132 offset:13952
	ds_read_b128 v[228:231], v132 offset:14016
	s_cselect_b32 s4, s57, s70
	s_waitcnt lgkmcnt(14)
	v_mfma_f32_16x16x32_bf16 v[124:127], v[124:127], v[12:15], v[16:19]
	v_mfma_f32_16x16x32_bf16 v[124:127], v[128:131], v[0:3], v[124:127]
	s_waitcnt lgkmcnt(13)
	v_mfma_f32_16x16x32_bf16 v[128:131], v[150:153], v[4:7], v[20:23]
	s_waitcnt lgkmcnt(12)
	v_mfma_f32_16x16x32_bf16 v[128:131], v[154:157], v[8:11], v[128:131]
	s_waitcnt lgkmcnt(11)
	v_mfma_f32_16x16x32_bf16 v[150:153], v[158:161], v[12:15], v[16:19]
	s_waitcnt lgkmcnt(9)
	v_mfma_f32_16x16x32_bf16 v[154:157], v[166:169], v[4:7], v[20:23]
	v_mfma_f32_16x16x32_bf16 v[150:153], v[162:165], v[0:3], v[150:153]
	s_waitcnt lgkmcnt(8)
	v_mfma_f32_16x16x32_bf16 v[154:157], v[170:173], v[8:11], v[154:157]
	s_waitcnt lgkmcnt(7)
	v_mfma_f32_16x16x32_bf16 v[158:161], v[174:177], v[12:15], v[16:19]
	s_waitcnt lgkmcnt(5)
	v_mfma_f32_16x16x32_bf16 v[162:165], v[182:185], v[4:7], v[20:23]
	s_waitcnt lgkmcnt(3)
	v_mfma_f32_16x16x32_bf16 v[166:169], v[216:219], v[12:15], v[16:19]
	s_waitcnt lgkmcnt(1)
	v_mfma_f32_16x16x32_bf16 v[170:173], v[224:227], v[4:7], v[20:23]
	v_mfma_f32_16x16x32_bf16 v[158:161], v[178:181], v[0:3], v[158:161]
	v_mfma_f32_16x16x32_bf16 v[162:165], v[186:189], v[8:11], v[162:165]
	v_mfma_f32_16x16x32_bf16 v[166:169], v[220:223], v[0:3], v[166:169]
	s_waitcnt lgkmcnt(0)
	v_mfma_f32_16x16x32_bf16 v[170:173], v[228:231], v[8:11], v[170:173]
	v_add_u32_e32 v132, s4, v120
	v_add_u32_e32 v190, v132, v121
	ds_read_b128 v[174:177], v190
	ds_read_b128 v[178:181], v190 offset:2048
	ds_read_b128 v[182:185], v190 offset:4096
	ds_read_b128 v[186:189], v190 offset:6144
	ds_read_b128 v[216:219], v190 offset:8192
	ds_read_b128 v[220:223], v190 offset:10240
	ds_read_b128 v[224:227], v190 offset:12288
	ds_read_b128 v[228:231], v190 offset:14336
	v_exp_f32_e32 v191, v124
	v_exp_f32_e32 v190, v128
	v_exp_f32_e32 v241, v125
	v_exp_f32_e32 v240, v129
	v_exp_f32_e32 v243, v126
	v_exp_f32_e32 v242, v130
	v_exp_f32_e32 v245, v127
	v_exp_f32_e32 v244, v131
	v_exp_f32_e32 v247, v150
	v_exp_f32_e32 v246, v154
	v_exp_f32_e32 v249, v151
	v_exp_f32_e32 v248, v155
	v_exp_f32_e32 v251, v152
	v_exp_f32_e32 v250, v156
	v_exp_f32_e32 v253, v153
	v_exp_f32_e32 v252, v157
	v_cvt_pk_bf16_f32 v124, v191, v241
	v_cvt_pk_bf16_f32 v125, v243, v245
	v_cvt_pk_bf16_f32 v126, v247, v249
	v_cvt_pk_bf16_f32 v127, v251, v253
	v_cvt_pk_bf16_f32 v128, v190, v240
	v_cvt_pk_bf16_f32 v129, v242, v244
	v_cvt_pk_bf16_f32 v130, v246, v248
	v_cvt_pk_bf16_f32 v131, v250, v252
	v_add_u32_e32 v132, v132, v119
	s_waitcnt lgkmcnt(7)
	v_mfma_f32_16x16x32_bf16 v[72:75], v[174:177], v[124:127], v[72:75]
	ds_read_b128 v[150:153], v132
	ds_read_b128 v[154:157], v132 offset:2048
	v_exp_f32_e32 v201, v158
	v_exp_f32_e32 v200, v162
	v_mfma_f32_16x16x32_bf16 v[84:87], v[174:177], v[128:131], v[84:87]
	v_exp_f32_e32 v203, v159
	v_exp_f32_e32 v202, v163
	v_exp_f32_e32 v163, v160
	s_waitcnt lgkmcnt(8)
	v_mfma_f32_16x16x32_bf16 v[68:71], v[178:181], v[124:127], v[68:71]
	v_exp_f32_e32 v162, v164
	v_exp_f32_e32 v164, v170
	v_exp_f32_e32 v167, v167
	v_mfma_f32_16x16x32_bf16 v[80:83], v[178:181], v[128:131], v[80:83]
	v_exp_f32_e32 v170, v172
	v_exp_f32_e32 v169, v169
	v_cvt_pk_bf16_f32 v158, v201, v203
	s_waitcnt lgkmcnt(7)
	v_mfma_f32_16x16x32_bf16 v[60:63], v[182:185], v[124:127], v[60:63]
	v_mfma_f32_16x16x32_bf16 v[76:79], v[182:185], v[128:131], v[76:79]
	ds_read_b128 v[174:177], v132 offset:4096
	ds_read_b128 v[178:181], v132 offset:6144
	ds_read_b128 v[182:185], v132 offset:8192
	ds_read_b128 v[232:235], v132 offset:10240
	s_waitcnt lgkmcnt(10)
	v_mfma_f32_16x16x32_bf16 v[56:59], v[186:189], v[124:127], v[56:59]
	v_mfma_f32_16x16x32_bf16 v[64:67], v[186:189], v[128:131], v[64:67]
	ds_read_b128 v[186:189], v132 offset:12288
	ds_read_b128 v[236:239], v132 offset:14336
	s_waitcnt lgkmcnt(11)
	v_mfma_f32_16x16x32_bf16 v[36:39], v[216:219], v[124:127], v[36:39]
	v_mfma_f32_16x16x32_bf16 v[52:55], v[216:219], v[128:131], v[52:55]
	v_exp_f32_e32 v217, v161
	v_exp_f32_e32 v216, v165
	v_exp_f32_e32 v165, v166
	s_waitcnt lgkmcnt(10)
	v_mfma_f32_16x16x32_bf16 v[32:35], v[220:223], v[124:127], v[32:35]
	v_exp_f32_e32 v166, v171
	v_exp_f32_e32 v171, v168
	v_exp_f32_e32 v168, v173
	v_mfma_f32_16x16x32_bf16 v[48:51], v[220:223], v[128:131], v[48:51]
	v_cvt_pk_bf16_f32 v159, v163, v217
	v_cvt_pk_bf16_f32 v160, v165, v167
	v_cvt_pk_bf16_f32 v161, v171, v169
	s_waitcnt lgkmcnt(9)
	v_mfma_f32_16x16x32_bf16 v[28:31], v[224:227], v[124:127], v[28:31]
	v_mfma_f32_16x16x32_bf16 v[44:47], v[224:227], v[128:131], v[44:47]
	s_waitcnt lgkmcnt(8)
	v_mfma_f32_16x16x32_bf16 v[24:27], v[228:231], v[124:127], v[24:27]
	v_cvt_pk_bf16_f32 v124, v200, v202
	v_cvt_pk_bf16_f32 v125, v162, v216
	v_cvt_pk_bf16_f32 v126, v164, v166
	v_mfma_f32_16x16x32_bf16 v[40:43], v[228:231], v[128:131], v[40:43]
	v_cvt_pk_bf16_f32 v127, v170, v168
	s_waitcnt lgkmcnt(7)
	v_mfma_f32_16x16x32_bf16 v[84:87], v[150:153], v[124:127], v[84:87]
	v_add_f32_e64 v128, v250, v252
	v_add_f32_e64 v129, v251, v253
	s_bitcmp1_b32 s5, 0
	v_pk_add_f32 v[130:131], v[170:171], v[168:169]
	s_waitcnt lgkmcnt(6)
	v_mfma_f32_16x16x32_bf16 v[80:83], v[154:157], v[124:127], v[80:83]
	s_cselect_b32 s4, s91, 0
	v_lshl_add_u64 v[106:107], v[106:107], 0, s[66:67]
	v_lshl_add_u64 v[108:109], v[108:109], 0, s[76:77]
	s_waitcnt lgkmcnt(5)
	v_mfma_f32_16x16x32_bf16 v[76:79], v[174:177], v[124:127], v[76:79]
	s_waitcnt lgkmcnt(4)
	v_mfma_f32_16x16x32_bf16 v[64:67], v[178:181], v[124:127], v[64:67]
	s_waitcnt lgkmcnt(3)
	v_mfma_f32_16x16x32_bf16 v[52:55], v[182:185], v[124:127], v[52:55]
	s_waitcnt lgkmcnt(2)
	v_mfma_f32_16x16x32_bf16 v[48:51], v[232:235], v[124:127], v[48:51]
	s_waitcnt lgkmcnt(1)
	v_mfma_f32_16x16x32_bf16 v[44:47], v[186:189], v[124:127], v[44:47]
	s_waitcnt lgkmcnt(0)
	v_mfma_f32_16x16x32_bf16 v[40:43], v[236:239], v[124:127], v[40:43]
	v_add_f32_e64 v124, v190, v240
	v_add_f32_e64 v125, v191, v241
	v_pk_add_f32 v[126:127], v[242:243], v[244:245]
	s_nop 0
	v_pk_add_f32 v[124:125], v[124:125], v[126:127]
	v_pk_add_f32 v[126:127], v[246:247], v[248:249]
	v_mfma_f32_16x16x32_bf16 v[72:75], v[150:153], v[158:161], v[72:75]
	v_add_f32_e64 v126, v126, v128
	v_add_f32_e64 v127, v127, v129
	v_pk_add_f32 v[128:129], v[162:163], v[216:217]
	v_pk_add_f32 v[124:125], v[124:125], v[126:127]
	v_pk_add_f32 v[126:127], v[200:201], v[202:203]
	v_mfma_f32_16x16x32_bf16 v[68:71], v[154:157], v[158:161], v[68:71]
	v_add_f32_e64 v126, v126, v128
	v_add_f32_e64 v127, v127, v129
	v_pk_add_f32 v[128:129], v[164:165], v[166:167]
	v_pk_add_f32 v[110:111], v[110:111], v[124:125]
	v_mfma_f32_16x16x32_bf16 v[60:63], v[174:177], v[158:161], v[60:63]
	v_add_f32_e64 v128, v128, v130
	v_add_f32_e64 v129, v129, v131
	v_add3_u32 v124, s4, v116, v117
	s_cselect_b32 s4, s57, s70
	v_mfma_f32_16x16x32_bf16 v[56:59], v[178:181], v[158:161], v[56:59]
	v_add_f32_e64 v126, v126, v128
	v_add_f32_e64 v127, v127, v129
	s_waitcnt vmcnt(2)
	ds_write_b128 v124, v[92:95]
	ds_write_b128 v124, v[88:91] offset:16
	v_add_u32_e32 v88, s4, v122
	v_mfma_f32_16x16x32_bf16 v[36:39], v[182:185], v[158:161], v[36:39]
	v_add_f32_e64 v110, v110, v126
	v_add_f32_e64 v111, v111, v127
	s_waitcnt vmcnt(0)
	ds_write_b128 v88, v[100:103]
	v_add_u32_e32 v88, s4, v123
	v_mfma_f32_16x16x32_bf16 v[32:35], v[232:235], v[158:161], v[32:35]
	s_cmp_lg_u32 s23, s5
	s_mov_b32 s4, s5
	ds_write_b128 v88, v[96:99]
	v_mfma_f32_16x16x32_bf16 v[28:31], v[186:189], v[158:161], v[28:31]
	s_waitcnt lgkmcnt(0)
	s_barrier
	v_mfma_f32_16x16x32_bf16 v[24:27], v[236:239], v[158:161], v[24:27]
	s_cbranch_scc1 .LBB0_131
	v_add_u32_e32 v116, 0, v118
	ds_read_b128 v[88:91], v116 offset:18432
	ds_read_b128 v[92:95], v116 offset:18496
	ds_read_b128 v[96:99], v116 offset:18560
	ds_read_b128 v[100:103], v116 offset:18624
	ds_read_b128 v[106:109], v116 offset:23040
	ds_read_b128 v[122:125], v116 offset:23104
	ds_read_b128 v[126:129], v116 offset:23168
	ds_read_b128 v[150:153], v116 offset:23232
	ds_read_b128 v[154:157], v116 offset:27648
	ds_read_b128 v[158:161], v116 offset:27712
	ds_read_b128 v[162:165], v116 offset:27776
	ds_read_b128 v[166:169], v116 offset:27840
	ds_read_b128 v[170:173], v116 offset:32256
	ds_read_b128 v[174:177], v116 offset:32320
	ds_read_b128 v[178:181], v116 offset:32384
	ds_read_b128 v[182:185], v116 offset:32448
	s_waitcnt lgkmcnt(14)
	v_mfma_f32_16x16x32_bf16 v[88:91], v[88:91], v[12:15], v[16:19]
	v_mfma_f32_16x16x32_bf16 v[88:91], v[92:95], v[0:3], v[88:91]
	s_waitcnt lgkmcnt(13)
	v_mfma_f32_16x16x32_bf16 v[92:95], v[96:99], v[4:7], v[20:23]
	s_waitcnt lgkmcnt(11)
	v_mfma_f32_16x16x32_bf16 v[96:99], v[106:109], v[12:15], v[16:19]
	v_mfma_f32_16x16x32_bf16 v[92:95], v[100:103], v[8:11], v[92:95]
	s_waitcnt lgkmcnt(10)
	v_mfma_f32_16x16x32_bf16 v[96:99], v[122:125], v[0:3], v[96:99]
	s_waitcnt lgkmcnt(9)
	v_mfma_f32_16x16x32_bf16 v[100:103], v[126:129], v[4:7], v[20:23]
	s_waitcnt lgkmcnt(7)
	v_mfma_f32_16x16x32_bf16 v[106:109], v[154:157], v[12:15], v[16:19]
	s_waitcnt lgkmcnt(5)
	v_mfma_f32_16x16x32_bf16 v[122:125], v[162:165], v[4:7], v[20:23]
	s_waitcnt lgkmcnt(3)
	v_mfma_f32_16x16x32_bf16 v[12:15], v[170:173], v[12:15], v[16:19]
	s_waitcnt lgkmcnt(1)
	v_mfma_f32_16x16x32_bf16 v[4:7], v[178:181], v[4:7], v[20:23]
	v_mfma_f32_16x16x32_bf16 v[100:103], v[150:153], v[8:11], v[100:103]
	v_mfma_f32_16x16x32_bf16 v[106:109], v[158:161], v[0:3], v[106:109]
	v_mfma_f32_16x16x32_bf16 v[122:125], v[166:169], v[8:11], v[122:125]
	v_mfma_f32_16x16x32_bf16 v[0:3], v[174:177], v[0:3], v[12:15]
	s_waitcnt lgkmcnt(0)
	v_mfma_f32_16x16x32_bf16 v[4:7], v[182:185], v[8:11], v[4:7]
	v_add_u32_e32 v116, 0, v120
	v_add_u32_e32 v117, v116, v121
	v_add_u32_e32 v118, 0xd000, v117
	ds_read_b128 v[8:11], v117 offset:53248
	ds_read_b128 v[12:15], v117 offset:55296
	ds_read_b128 v[16:19], v117 offset:57344
	ds_read_b128 v[20:23], v117 offset:59392
	ds_read_b128 v[126:129], v117 offset:61440
	ds_read_b128 v[150:153], v117 offset:63488
	ds_read_b128 v[154:157], v118 offset:12288
	ds_read_b128 v[158:161], v118 offset:14336
	v_exp_f32_e32 v120, v88
	v_exp_f32_e32 v130, v92
	v_exp_f32_e32 v166, v89
	v_exp_f32_e32 v168, v93
	v_exp_f32_e32 v170, v90
	v_exp_f32_e32 v172, v94
	v_exp_f32_e32 v174, v91
	v_exp_f32_e32 v176, v95
	v_exp_f32_e32 v178, v96
	v_exp_f32_e32 v180, v100
	v_exp_f32_e32 v182, v97
	v_exp_f32_e32 v184, v101
	v_exp_f32_e32 v186, v98
	v_exp_f32_e32 v188, v102
	v_exp_f32_e32 v190, v99
	v_exp_f32_e32 v200, v103
	s_nop 0
	v_cvt_pk_bf16_f32 v88, v120, v166
	s_nop 0
	v_cvt_pk_bf16_f32 v89, v170, v174
	s_nop 0
	v_cvt_pk_bf16_f32 v90, v178, v182
	s_nop 0
	v_cvt_pk_bf16_f32 v91, v186, v190
	s_nop 0
	v_cvt_pk_bf16_f32 v92, v130, v168
	s_nop 0
	v_cvt_pk_bf16_f32 v93, v172, v176
	s_nop 0
	v_cvt_pk_bf16_f32 v94, v180, v184
	s_nop 0
	v_cvt_pk_bf16_f32 v95, v188, v200
	v_add_u32_e32 v121, v116, v119
	s_waitcnt lgkmcnt(7)
	v_mfma_f32_16x16x32_bf16 v[72:75], v[8:11], v[88:91], v[72:75]
	v_add_u32_e32 v131, 0xd000, v121
	v_exp_f32_e32 v167, v107
	v_exp_f32_e32 v169, v123
	v_mfma_f32_16x16x32_bf16 v[8:11], v[8:11], v[92:95], v[84:87]
	v_exp_f32_e32 v171, v108
	v_exp_f32_e32 v173, v124
	v_exp_f32_e32 v175, v109
	s_waitcnt lgkmcnt(6)
	v_mfma_f32_16x16x32_bf16 v[68:71], v[12:15], v[88:91], v[68:71]
	v_exp_f32_e32 v177, v125
	v_exp_f32_e32 v179, v0
	v_exp_f32_e32 v181, v4
	v_mfma_f32_16x16x32_bf16 v[12:15], v[12:15], v[92:95], v[80:83]
	v_exp_f32_e32 v183, v1
	v_exp_f32_e32 v185, v5
	v_exp_f32_e32 v187, v2
	s_waitcnt lgkmcnt(5)
	v_mfma_f32_16x16x32_bf16 v[60:63], v[16:19], v[88:91], v[60:63]
	v_exp_f32_e32 v189, v6
	v_exp_f32_e32 v191, v3
	v_exp_f32_e32 v201, v7
	v_mfma_f32_16x16x32_bf16 v[16:19], v[16:19], v[92:95], v[76:79]
	s_nop 2
	ds_read_b128 v[76:79], v121 offset:53248
	ds_read_b128 v[80:83], v121 offset:55296
	ds_read_b128 v[84:87], v121 offset:57344
	ds_read_b128 v[96:99], v121 offset:59392
	ds_read_b128 v[100:103], v121 offset:61440
	ds_read_b128 v[116:119], v121 offset:63488
	s_nop 0
	v_cvt_pk_bf16_f32 v1, v171, v175
	s_waitcnt lgkmcnt(10)
	v_mfma_f32_16x16x32_bf16 v[56:59], v[20:23], v[88:91], v[56:59]
	s_nop 0
	v_cvt_pk_bf16_f32 v2, v179, v183
	s_nop 0
	v_cvt_pk_bf16_f32 v3, v187, v191
	v_mfma_f32_16x16x32_bf16 v[20:23], v[20:23], v[92:95], v[64:67]
	s_nop 2
	ds_read_b128 v[64:67], v131 offset:12288
	ds_read_b128 v[162:165], v131 offset:14336
	v_exp_f32_e32 v121, v106
	v_exp_f32_e32 v131, v122
	s_waitcnt lgkmcnt(11)
	v_mfma_f32_16x16x32_bf16 v[36:39], v[126:129], v[88:91], v[36:39]
	s_nop 0
	v_cvt_pk_bf16_f32 v0, v121, v167
	v_mfma_f32_16x16x32_bf16 v[52:55], v[126:129], v[92:95], v[52:55]
	s_waitcnt lgkmcnt(10)
	v_mfma_f32_16x16x32_bf16 v[32:35], v[150:153], v[88:91], v[32:35]
	v_mfma_f32_16x16x32_bf16 v[48:51], v[150:153], v[92:95], v[48:51]
	s_waitcnt lgkmcnt(9)
	v_mfma_f32_16x16x32_bf16 v[28:31], v[154:157], v[88:91], v[28:31]
	v_mfma_f32_16x16x32_bf16 v[4:7], v[154:157], v[92:95], v[44:47]
	s_nop 0
	v_cvt_pk_bf16_f32 v44, v131, v169
	s_nop 0
	v_cvt_pk_bf16_f32 v45, v173, v177
	s_nop 0
	v_cvt_pk_bf16_f32 v46, v181, v185
	s_waitcnt lgkmcnt(8)
	v_mfma_f32_16x16x32_bf16 v[24:27], v[158:161], v[88:91], v[24:27]
	s_nop 0
	v_cvt_pk_bf16_f32 v47, v189, v201
	v_mfma_f32_16x16x32_bf16 v[40:43], v[158:161], v[92:95], v[40:43]
	s_waitcnt lgkmcnt(7)
	v_mfma_f32_16x16x32_bf16 v[72:75], v[76:79], v[0:3], v[72:75]
	s_waitcnt lgkmcnt(0)
	s_barrier
	v_mfma_f32_16x16x32_bf16 v[8:11], v[76:79], v[44:47], v[8:11]
	v_add_f32_e64 v76, v130, v168
	v_add_f32_e64 v77, v131, v169
	v_pk_add_f32 v[78:79], v[172:173], v[176:177]
	v_mfma_f32_16x16x32_bf16 v[68:71], v[80:83], v[0:3], v[68:71]
	v_add_f32_e64 v76, v76, v78
	v_add_f32_e64 v77, v77, v79
	v_pk_add_f32 v[78:79], v[180:181], v[184:185]
	v_mfma_f32_16x16x32_bf16 v[12:15], v[80:83], v[44:47], v[12:15]
	v_add_f32_e64 v80, v188, v200
	v_add_f32_e64 v81, v189, v201
	v_pk_add_f32 v[78:79], v[78:79], v[80:81]
	v_pk_add_f32 v[80:81], v[186:187], v[190:191]
	v_pk_add_f32 v[76:77], v[76:77], v[78:79]
	v_pk_add_f32 v[78:79], v[170:171], v[174:175]
	v_add_f32_e32 v76, v110, v76
	v_add_f32_e32 v82, v76, v77
	v_pk_add_f32 v[76:77], v[120:121], v[166:167]
	v_mfma_f32_16x16x32_bf16 v[28:31], v[64:67], v[0:3], v[28:31]
	v_add_f32_e64 v76, v76, v78
	v_add_f32_e64 v77, v77, v79
	v_pk_add_f32 v[78:79], v[178:179], v[182:183]
	v_mfma_f32_16x16x32_bf16 v[64:67], v[64:67], v[44:47], v[4:7]
	s_nop 2
	v_add_f32_e64 v4, v78, v80
	v_add_f32_e64 v5, v79, v81
	v_mfma_f32_16x16x32_bf16 v[60:63], v[84:87], v[0:3], v[60:63]
	v_add_f32_e64 v4, v76, v4
	v_add_f32_e64 v5, v77, v5
	v_add_f32_e32 v4, v111, v4
	v_mfma_f32_16x16x32_bf16 v[16:19], v[84:87], v[44:47], v[16:19]
	v_mfma_f32_16x16x32_bf16 v[56:59], v[96:99], v[0:3], v[56:59]
	v_mfma_f32_16x16x32_bf16 v[20:23], v[96:99], v[44:47], v[20:23]
	v_mfma_f32_16x16x32_bf16 v[36:39], v[100:103], v[0:3], v[36:39]
	v_mfma_f32_16x16x32_bf16 v[52:55], v[100:103], v[44:47], v[52:55]
	v_mfma_f32_16x16x32_bf16 v[32:35], v[116:119], v[0:3], v[32:35]
	v_mfma_f32_16x16x32_bf16 v[48:51], v[116:119], v[44:47], v[48:51]
	v_mfma_f32_16x16x32_bf16 v[24:27], v[162:165], v[0:3], v[24:27]
	v_add_f32_e32 v0, v4, v5
	v_mfma_f32_16x16x32_bf16 v[40:43], v[162:165], v[44:47], v[40:43]
	s_setprio 0
	ds_bpermute_b32 v1, v114, v0
	ds_bpermute_b32 v2, v114, v82
	s_waitcnt lgkmcnt(1)
	v_add_f32_e32 v0, v0, v1
	s_waitcnt lgkmcnt(0)
	v_add_f32_e32 v1, v82, v2
	ds_bpermute_b32 v2, v115, v0
	ds_bpermute_b32 v3, v115, v1
	s_waitcnt lgkmcnt(1)
	v_add_f32_e32 v0, v0, v2
	v_div_scale_f32 v2, s[4:5], v0, v0, 1.0
	v_rcp_f32_e32 v4, v2
	s_waitcnt lgkmcnt(0)
	v_add_f32_e32 v1, v1, v3
	v_div_scale_f32 v3, vcc, 1.0, v0, 1.0
	v_fma_f32 v7, -v2, v4, 1.0
	v_fmac_f32_e32 v4, v7, v4
	v_div_scale_f32 v5, s[4:5], v1, v1, v113
	v_mul_f32_e32 v7, v3, v4
	v_rcp_f32_e32 v6, v5
	v_fma_f32 v44, -v2, v7, v3
	v_fmac_f32_e32 v7, v44, v4
	v_fma_f32 v2, -v2, v7, v3
	v_div_fmas_f32 v2, v2, v4, v7
	v_div_fixup_f32 v44, v2, v0, 1.0
	v_fma_f32 v0, -v5, v6, 1.0
	v_fmac_f32_e32 v6, v0, v6
	v_div_scale_f32 v0, vcc, v113, v1, v113
	v_mul_f32_e32 v2, v0, v6
	v_fma_f32 v3, -v5, v2, v0
	v_fmac_f32_e32 v2, v3, v6
	v_fma_f32 v0, -v5, v2, v0
	v_div_fmas_f32 v0, v0, v6, v2
	s_mov_b64 s[4:5], s[0:1]
	v_div_fixup_f32 v46, v0, v1, v113
	v_pk_mul_f32 v[0:1], v[8:9], v[46:47] op_sel_hi:[1,0]
	v_pk_mul_f32 v[2:3], v[10:11], v[46:47] op_sel_hi:[1,0]
	s_load_dwordx2 s[4:5], s[4:5], 0x78
	v_pk_fma_f32 v[74:75], v[74:75], v[44:45], v[2:3] op_sel_hi:[1,0,1] neg_lo:[0,0,1] neg_hi:[0,0,1]
	v_pk_fma_f32 v[72:73], v[72:73], v[44:45], v[0:1] op_sel_hi:[1,0,1] neg_lo:[0,0,1] neg_hi:[0,0,1]
	v_pk_mul_f32 v[0:1], v[12:13], v[46:47] op_sel_hi:[1,0]
	v_pk_mul_f32 v[2:3], v[14:15], v[46:47] op_sel_hi:[1,0]
	v_pk_fma_f32 v[68:69], v[68:69], v[44:45], v[0:1] op_sel_hi:[1,0,1] neg_lo:[0,0,1] neg_hi:[0,0,1]
	v_pk_fma_f32 v[70:71], v[70:71], v[44:45], v[2:3] op_sel_hi:[1,0,1] neg_lo:[0,0,1] neg_hi:[0,0,1]
	v_pk_mul_f32 v[0:1], v[16:17], v[46:47] op_sel_hi:[1,0]
	v_pk_mul_f32 v[2:3], v[18:19], v[46:47] op_sel_hi:[1,0]
	v_pk_fma_f32 v[60:61], v[60:61], v[44:45], v[0:1] op_sel_hi:[1,0,1] neg_lo:[0,0,1] neg_hi:[0,0,1]
	v_pk_fma_f32 v[16:17], v[62:63], v[44:45], v[2:3] op_sel_hi:[1,0,1] neg_lo:[0,0,1] neg_hi:[0,0,1]
	v_pk_mul_f32 v[0:1], v[20:21], v[46:47] op_sel_hi:[1,0]
	v_pk_mul_f32 v[2:3], v[22:23], v[46:47] op_sel_hi:[1,0]
	v_pk_fma_f32 v[14:15], v[56:57], v[44:45], v[0:1] op_sel_hi:[1,0,1] neg_lo:[0,0,1] neg_hi:[0,0,1]
	v_pk_fma_f32 v[12:13], v[58:59], v[44:45], v[2:3] op_sel_hi:[1,0,1] neg_lo:[0,0,1] neg_hi:[0,0,1]
	v_pk_mul_f32 v[0:1], v[52:53], v[46:47] op_sel_hi:[1,0]
	v_pk_mul_f32 v[2:3], v[54:55], v[46:47] op_sel_hi:[1,0]
	v_pk_fma_f32 v[10:11], v[36:37], v[44:45], v[0:1] op_sel_hi:[1,0,1] neg_lo:[0,0,1] neg_hi:[0,0,1]
	v_pk_fma_f32 v[8:9], v[38:39], v[44:45], v[2:3] op_sel_hi:[1,0,1] neg_lo:[0,0,1] neg_hi:[0,0,1]
	v_pk_mul_f32 v[0:1], v[48:49], v[46:47] op_sel_hi:[1,0]
	v_pk_mul_f32 v[2:3], v[50:51], v[46:47] op_sel_hi:[1,0]
	s_waitcnt lgkmcnt(0)
	s_add_u32 s4, s4, s8
	v_pk_fma_f32 v[4:5], v[34:35], v[44:45], v[2:3] op_sel_hi:[1,0,1] neg_lo:[0,0,1] neg_hi:[0,0,1]
	v_pk_fma_f32 v[6:7], v[32:33], v[44:45], v[0:1] op_sel_hi:[1,0,1] neg_lo:[0,0,1] neg_hi:[0,0,1]
	v_pk_mul_f32 v[2:3], v[64:65], v[46:47] op_sel_hi:[1,0]
	v_pk_mul_f32 v[0:1], v[66:67], v[46:47] op_sel_hi:[1,0]
	v_pk_mul_f32 v[18:19], v[40:41], v[46:47] op_sel_hi:[1,0]
	v_pk_mul_f32 v[20:21], v[42:43], v[46:47] op_sel_hi:[1,0]
	s_addc_u32 s5, s5, s9
	v_lshlrev_b32_e32 v46, 4, v105
	v_pk_fma_f32 v[0:1], v[30:31], v[44:45], v[0:1] op_sel_hi:[1,0,1] neg_lo:[0,0,1] neg_hi:[0,0,1]
	v_pk_fma_f32 v[2:3], v[28:29], v[44:45], v[2:3] op_sel_hi:[1,0,1] neg_lo:[0,0,1] neg_hi:[0,0,1]
	v_pk_fma_f32 v[50:51], v[26:27], v[44:45], v[20:21] op_sel_hi:[1,0,1] neg_lo:[0,0,1] neg_hi:[0,0,1]
	v_pk_fma_f32 v[52:53], v[24:25], v[44:45], v[18:19] op_sel_hi:[1,0,1] neg_lo:[0,0,1] neg_hi:[0,0,1]
	global_load_dwordx4 v[18:21], v46, s[4:5]
	global_load_dwordx4 v[22:25], v46, s[4:5] offset:64
	global_load_dwordx4 v[26:29], v46, s[4:5] offset:128
	global_load_dwordx4 v[30:33], v46, s[4:5] offset:192
	global_load_dwordx4 v[34:37], v46, s[4:5] offset:256
	global_load_dwordx4 v[38:41], v46, s[4:5] offset:320
	global_load_dwordx4 v[42:45], v46, s[4:5] offset:384
	s_nop 0
	global_load_dwordx4 v[46:49], v46, s[4:5] offset:448
	v_mov_b32_e32 v56, v73
	v_mov_b32_e32 v57, v69
	v_mov_b32_e32 v54, v72
	v_mov_b32_e32 v55, v68
	v_pk_mul_f32 v[56:57], v[56:57], v[56:57]
	v_mov_b32_e32 v58, v15
	v_pk_fma_f32 v[54:55], v[54:55], v[54:55], v[56:57]
	v_mov_b32_e32 v56, v74
	v_mov_b32_e32 v57, v70
	v_pk_fma_f32 v[54:55], v[56:57], v[56:57], v[54:55]
	v_mov_b32_e32 v56, v75
	v_mov_b32_e32 v57, v71
	v_mov_b32_e32 v59, v61
	v_pk_fma_f32 v[54:55], v[56:57], v[56:57], v[54:55]
	v_mov_b32_e32 v56, v14
	v_mov_b32_e32 v57, v60
	v_pk_mul_f32 v[58:59], v[58:59], v[58:59]
	v_mov_b32_e32 v62, v7
	v_pk_fma_f32 v[56:57], v[56:57], v[56:57], v[58:59]
	v_mov_b32_e32 v58, v12
	v_mov_b32_e32 v59, v16
	v_pk_fma_f32 v[56:57], v[58:59], v[58:59], v[56:57]
	v_mov_b32_e32 v58, v13
	v_mov_b32_e32 v59, v17
	v_mov_b32_e32 v63, v11
	v_pk_fma_f32 v[56:57], v[58:59], v[58:59], v[56:57]
	v_mov_b32_e32 v58, v6
	v_mov_b32_e32 v59, v10
	v_pk_mul_f32 v[62:63], v[62:63], v[62:63]
	v_mov_b32_e32 v64, v53
	v_pk_fma_f32 v[58:59], v[58:59], v[58:59], v[62:63]
	v_mov_b32_e32 v62, v4
	v_mov_b32_e32 v63, v8
	v_pk_fma_f32 v[58:59], v[62:63], v[62:63], v[58:59]
	v_mov_b32_e32 v62, v5
	v_mov_b32_e32 v63, v9
	v_mov_b32_e32 v65, v3
	v_add_f32_e32 v54, v54, v55
	v_pk_fma_f32 v[58:59], v[62:63], v[62:63], v[58:59]
	v_mov_b32_e32 v62, v52
	v_mov_b32_e32 v63, v2
	v_pk_mul_f32 v[64:65], v[64:65], v[64:65]
	v_add_f32_e32 v54, v57, v54
	v_pk_fma_f32 v[62:63], v[62:63], v[62:63], v[64:65]
	v_mov_b32_e32 v64, v50
	v_mov_b32_e32 v65, v0
	v_add_f32_e32 v54, v56, v54
	v_pk_fma_f32 v[62:63], v[64:65], v[64:65], v[62:63]
	v_mov_b32_e32 v64, v51
	v_mov_b32_e32 v65, v1
	v_add_f32_e32 v54, v59, v54
	v_pk_fma_f32 v[62:63], v[64:65], v[64:65], v[62:63]
	v_add_f32_e32 v54, v58, v54
	v_add_f32_e32 v54, v63, v54
	v_add_f32_e32 v54, v62, v54
	ds_bpermute_b32 v55, v114, v54
	v_sub_f32_e32 v56, 1.0, v112
	s_waitcnt lgkmcnt(0)
	v_add_f32_e32 v54, v54, v55
	ds_bpermute_b32 v55, v115, v54
	s_waitcnt lgkmcnt(0)
	v_add_f32_e32 v54, v54, v55
	v_fmamk_f32 v54, v54, 0x3c000000, v137
	v_mul_f32_e32 v55, 0x4b800000, v54
	v_cmp_gt_f32_e32 vcc, s94, v54
	s_nop 1
	v_cndmask_b32_e32 v54, v54, v55, vcc
	v_rsq_f32_e32 v54, v54
	s_nop 0
	v_mul_f32_e32 v55, 0x45800000, v54
	v_cndmask_b32_e32 v54, v54, v55, vcc
	v_mul_f32_e32 v54, v56, v54
	v_mov_b64_e32 v[56:57], s[12:13]
	v_mad_i64_i32 v[56:57], s[4:5], v104, s96, v[56:57]
	s_lshl_b32 s58, s22, 1
	v_pk_mul_f32 v[58:59], v[72:73], v[54:55] op_sel_hi:[1,0]
	v_lshl_add_u64 v[56:57], v[56:57], 0, s[58:59]
	v_lshlrev_b32_e32 v132, 3, v105
	v_pk_mul_f32 v[62:63], v[74:75], v[54:55] op_sel_hi:[1,0]
	s_waitcnt vmcnt(7)
	v_pk_mul_f32 v[18:19], v[18:19], v[58:59]
	v_lshl_add_u64 v[56:57], v[56:57], 0, v[132:133]
	v_pk_mul_f32 v[20:21], v[20:21], v[62:63]
	v_cvt_pk_bf16_f32 v18, v18, v19
	v_pk_mul_f32 v[2:3], v[2:3], v[54:55] op_sel_hi:[1,0]
	v_cvt_pk_bf16_f32 v19, v20, v21
	global_store_dwordx2 v[56:57], v[18:19], off
	v_pk_mul_f32 v[18:19], v[68:69], v[54:55] op_sel_hi:[1,0]
	v_pk_mul_f32 v[20:21], v[70:71], v[54:55] op_sel_hi:[1,0]
	s_waitcnt vmcnt(7)
	v_pk_mul_f32 v[18:19], v[22:23], v[18:19]
	v_pk_mul_f32 v[0:1], v[0:1], v[54:55] op_sel_hi:[1,0]
	v_pk_mul_f32 v[20:21], v[24:25], v[20:21]
	v_cvt_pk_bf16_f32 v18, v18, v19
	s_waitcnt vmcnt(2)
	v_pk_mul_f32 v[0:1], v[44:45], v[0:1]
	v_cvt_pk_bf16_f32 v19, v20, v21
	v_pk_mul_f32 v[2:3], v[42:43], v[2:3]
	global_store_dwordx2 v[56:57], v[18:19], off offset:32
	v_pk_mul_f32 v[18:19], v[60:61], v[54:55] op_sel_hi:[1,0]
	v_pk_mul_f32 v[14:15], v[14:15], v[54:55] op_sel_hi:[1,0]
	v_pk_mul_f32 v[10:11], v[10:11], v[54:55] op_sel_hi:[1,0]
	v_pk_mul_f32 v[6:7], v[6:7], v[54:55] op_sel_hi:[1,0]
	v_cvt_pk_bf16_f32 v2, v2, v3
	v_cvt_pk_bf16_f32 v3, v0, v1
	v_pk_mul_f32 v[0:1], v[52:53], v[54:55] op_sel_hi:[1,0]
	v_pk_mul_f32 v[16:17], v[16:17], v[54:55] op_sel_hi:[1,0]
	v_pk_mul_f32 v[18:19], v[26:27], v[18:19]
	v_pk_mul_f32 v[12:13], v[12:13], v[54:55] op_sel_hi:[1,0]
	v_pk_mul_f32 v[14:15], v[30:31], v[14:15]
	v_pk_mul_f32 v[8:9], v[8:9], v[54:55] op_sel_hi:[1,0]
	v_pk_mul_f32 v[10:11], v[34:35], v[10:11]
	v_pk_mul_f32 v[4:5], v[4:5], v[54:55] op_sel_hi:[1,0]
	v_pk_mul_f32 v[6:7], v[38:39], v[6:7]
	global_store_dwordx2 v[56:57], v[2:3], off offset:192
	v_pk_mul_f32 v[2:3], v[50:51], v[54:55] op_sel_hi:[1,0]
	s_waitcnt vmcnt(3)
	v_pk_mul_f32 v[0:1], v[46:47], v[0:1]
	s_mov_b64 s[4:5], 0
	v_pk_mul_f32 v[16:17], v[28:29], v[16:17]
	v_cvt_pk_bf16_f32 v18, v18, v19
	v_pk_mul_f32 v[12:13], v[32:33], v[12:13]
	v_cvt_pk_bf16_f32 v19, v16, v17
	global_store_dwordx2 v[56:57], v[18:19], off offset:64
	v_cvt_pk_bf16_f32 v14, v14, v15
	v_cvt_pk_bf16_f32 v15, v12, v13
	global_store_dwordx2 v[56:57], v[14:15], off offset:96
	v_pk_mul_f32 v[8:9], v[36:37], v[8:9]
	v_cvt_pk_bf16_f32 v10, v10, v11
	v_pk_mul_f32 v[4:5], v[40:41], v[4:5]
	v_cvt_pk_bf16_f32 v11, v8, v9
	global_store_dwordx2 v[56:57], v[10:11], off offset:128
	v_cvt_pk_bf16_f32 v6, v6, v7
	v_cvt_pk_bf16_f32 v7, v4, v5
	global_store_dwordx2 v[56:57], v[6:7], off offset:160
	v_pk_mul_f32 v[2:3], v[48:49], v[2:3]
	v_cvt_pk_bf16_f32 v0, v0, v1
	s_nop 0
	v_cvt_pk_bf16_f32 v1, v2, v3
	global_store_dwordx2 v[56:57], v[0:1], off offset:224
	s_branch .LBB0_77
